# non-temporal hint on the once-read f32 weight loads in the transpose loops (on top of idle-time weight conversion)
# speedup vs baseline: 1.0046x; 1.0046x over previous
; __device__ __forceinline__ void transpose_item(const float* __restrict__ W, int ld_src, int k0, int n0src, const float* __restrict__ kscale, bf16_t* __restrict__ WT, int ldt, int n0dst, LAS float* scr, int lane) {
; #pragma unroll 8
;     for (int i = 0; i < 32; ++i) { const int kk = 2 * i + (lane >> 5); float v = W[(size_t)(k0 + kk) * ld_src + n0src + (lane & 31)]; if (kscale) v *= kscale[k0 + kk]; scr[kk * 33 + (lane & 31)] = v; }
; __global__ void __launch_bounds__(512, 2) mk_fwd(Args args) {
;     ...
;             { const int db = r / 4, nb = r % 4;
;               transpose_item(w_gate + ((size_t)L * 32 + db) * 64 * 128, 128, 0, nb * 32, nullptr, WG + ((size_t)L * 32 + db) * 128 * 64, 64, nb * 32, scr, lane); }
.LBB0_15:
	s_lshl_b32 s38, s14, 1
	s_lshl_b32 s39, s15, 1
	v_or_b32_e32 v4, s39, v2
	s_add_i32 s40, s38, 4
	s_add_i32 s41, s39, 4
	v_mov_b32_e32 v33, v5
	v_or_b32_e32 v30, s38, v1
	s_add_i32 s42, s38, 8
	s_add_i32 s43, s39, 8
	s_add_i32 s44, s38, 12
	s_add_i32 s45, s39, 12
	s_add_i32 s46, s38, 16
	s_add_i32 s47, s39, 16
	s_add_i32 s48, s38, 20
	s_add_i32 s49, s39, 20
	s_add_i32 s50, s38, 24
	s_add_i32 s51, s39, 24
	s_add_i32 s52, s38, 28
	s_add_i32 s53, s39, 28
	v_lshlrev_b64 v[64:65], 9, v[4:5]
	v_mad_u64_u32 v[66:67], s[38:39], v4, s18, v[12:13]
	v_or_b32_e32 v32, s40, v1
	v_or_b32_e32 v4, s41, v2
	v_mov_b32_e32 v31, v5
	v_lshlrev_b64 v[68:69], 9, v[32:33]
	v_lshlrev_b64 v[70:71], 9, v[4:5]
	v_mad_u64_u32 v[72:73], s[38:39], v4, s18, v[12:13]
	v_or_b32_e32 v4, s43, v2
	v_lshlrev_b64 v[46:47], 9, v[30:31]
	v_lshl_add_u64 v[64:65], v[28:29], 0, v[64:65]
	v_lshl_add_u64 v[68:69], v[28:29], 0, v[68:69]
	v_lshlrev_b64 v[86:87], 9, v[4:5]
	v_mad_u64_u32 v[88:89], s[38:39], v4, s18, v[12:13]
	v_or_b32_e32 v4, s45, v2
	v_mov_b32_e32 v35, v5
	v_mov_b32_e32 v37, v5
	v_or_b32_e32 v34, s42, v1
	v_or_b32_e32 v36, s44, v1
	v_lshl_add_u64 v[46:47], v[28:29], 0, v[46:47]
	v_lshl_add_u64 v[70:71], v[28:29], 0, v[70:71]
	global_load_dword v27, v[64:65], off nt
	global_load_dword v63, v[46:47], off nt
	global_load_dword v67, v[70:71], off nt
	global_load_dword v73, v[68:69], off nt
	v_lshlrev_b64 v[64:65], 9, v[4:5]
	v_mad_u64_u32 v[68:69], s[38:39], v4, s18, v[12:13]
	v_or_b32_e32 v4, s47, v2
	v_mov_b32_e32 v39, v5
	v_or_b32_e32 v38, s46, v1
	v_lshlrev_b64 v[74:75], 9, v[34:35]
	v_lshlrev_b64 v[76:77], 9, v[36:37]
	v_lshl_add_u64 v[46:47], v[28:29], 0, v[86:87]
	v_lshl_add_u64 v[64:65], v[28:29], 0, v[64:65]
	v_lshlrev_b64 v[70:71], 9, v[4:5]
	v_mad_u64_u32 v[86:87], s[38:39], v4, s18, v[12:13]
	v_or_b32_e32 v4, s49, v2
	v_mov_b32_e32 v41, v5
	v_or_b32_e32 v40, s48, v1
	v_lshlrev_b64 v[78:79], 9, v[38:39]
	v_lshl_add_u64 v[74:75], v[28:29], 0, v[74:75]
	v_lshl_add_u64 v[76:77], v[28:29], 0, v[76:77]
	global_load_dword v69, v[46:47], off nt
	global_load_dword v87, v[74:75], off nt
	global_load_dword v89, v[64:65], off nt
	global_load_dword v90, v[76:77], off nt
	v_lshl_add_u64 v[46:47], v[28:29], 0, v[70:71]
	v_lshlrev_b64 v[64:65], 9, v[4:5]
	v_mad_u64_u32 v[70:71], s[38:39], v4, s18, v[12:13]
	v_or_b32_e32 v4, s51, v2
	v_lshlrev_b64 v[80:81], 9, v[40:41]
	v_lshl_add_u64 v[78:79], v[28:29], 0, v[78:79]
	v_lshl_add_u64 v[64:65], v[28:29], 0, v[64:65]
	v_lshlrev_b64 v[74:75], 9, v[4:5]
	v_mad_u64_u32 v[76:77], s[38:39], v4, s18, v[12:13]
	v_or_b32_e32 v4, s53, v2
	v_mov_b32_e32 v43, v5
	v_mov_b32_e32 v45, v5
	v_or_b32_e32 v42, s50, v1
	v_or_b32_e32 v44, s52, v1
	v_lshl_add_u64 v[80:81], v[28:29], 0, v[80:81]
	global_load_dword v71, v[46:47], off nt
	global_load_dword v77, v[78:79], off nt
	s_nop 0
	global_load_dword v78, v[64:65], off nt
	global_load_dword v79, v[80:81], off nt
	v_lshlrev_b64 v[64:65], 9, v[4:5]
	v_lshlrev_b64 v[82:83], 9, v[42:43]
	v_lshlrev_b64 v[84:85], 9, v[44:45]
	v_lshl_add_u64 v[46:47], v[28:29], 0, v[74:75]
	v_lshl_add_u64 v[64:65], v[28:29], 0, v[64:65]
	v_lshl_add_u64 v[82:83], v[28:29], 0, v[82:83]
	v_lshl_add_u64 v[84:85], v[28:29], 0, v[84:85]
	global_load_dword v74, v[46:47], off nt
	global_load_dword v75, v[82:83], off nt
	s_nop 0
	global_load_dword v64, v[64:65], off nt
	s_nop 0
	global_load_dword v65, v[84:85], off nt
	s_add_i32 s15, s15, 16
	s_add_i32 s14, s14, 16
	s_add_i32 s37, s37, -16
	s_cmp_lg_u32 s37, 0
	v_mad_u64_u32 v[30:31], s[38:39], v30, s18, v[12:13]
	v_mad_u64_u32 v[32:33], s[38:39], v32, s18, v[12:13]
	v_mad_u64_u32 v[34:35], s[38:39], v34, s18, v[12:13]
	v_mad_u64_u32 v[36:37], s[38:39], v36, s18, v[12:13]
	v_mad_u64_u32 v[38:39], s[38:39], v38, s18, v[12:13]
	v_mad_u64_u32 v[40:41], s[38:39], v40, s18, v[12:13]
	v_mad_u64_u32 v[42:43], s[38:39], v42, s18, v[12:13]
	v_mad_u64_u32 v[44:45], s[38:39], v44, s18, v[12:13]
	v_mad_u64_u32 v[46:47], s[38:39], v4, s18, v[12:13]
	s_waitcnt vmcnt(15)
	ds_write_b32 v66, v27
	s_waitcnt vmcnt(14)
	ds_write_b32 v30, v63
	s_waitcnt vmcnt(13)
	ds_write_b32 v72, v67
	s_waitcnt vmcnt(12)
	ds_write_b32 v32, v73
	s_waitcnt vmcnt(11)
	ds_write_b32 v88, v69
	s_waitcnt vmcnt(10)
	ds_write_b32 v34, v87
	s_waitcnt vmcnt(9)
	ds_write_b32 v68, v89
	s_waitcnt vmcnt(8)
	ds_write_b32 v36, v90
	s_waitcnt vmcnt(7)
	ds_write_b32 v86, v71
	s_waitcnt vmcnt(6)
	ds_write_b32 v38, v77
	s_waitcnt vmcnt(5)
	ds_write_b32 v70, v78
	s_waitcnt vmcnt(4)
	ds_write_b32 v40, v79
	s_waitcnt vmcnt(3)
	ds_write_b32 v76, v74
	s_waitcnt vmcnt(2)
	ds_write_b32 v42, v75
	s_waitcnt vmcnt(1)
	ds_write_b32 v46, v64
	s_waitcnt vmcnt(0)
	ds_write_b32 v44, v65
	s_cbranch_scc1 .LBB0_15
; #define LAS __attribute__((address_space(3)))
; __device__ __forceinline__ unsigned cvt_pk(float lo, float hi) { f32x2_t v = {lo, hi}; bf16x2_t b = __builtin_convertvector(v, bf16x2_t); return __builtin_bit_cast(unsigned, b); }
; __device__ __forceinline__ void transpose_item(const float* __restrict__ W, int ld_src, int k0, int n0src, const float* __restrict__ kscale, bf16_t* __restrict__ WT, int ldt, int n0dst, LAS float* scr, int lane) {
;     ...
;     asm volatile("s_waitcnt lgkmcnt(0)" ::: "memory"); __builtin_amdgcn_wave_barrier();
;     const int c = lane & 7;
; #pragma unroll
;     for (int jn = 0; jn < 4; ++jn) { const int n = (lane >> 3) + 8 * jn; const LAS float* s = scr + (8 * c) * 33 + n;
;         u32x4 o; o.x = cvt_pk(s[0 * 33], s[1 * 33]); o.y = cvt_pk(s[2 * 33], s[3 * 33]); o.z = cvt_pk(s[4 * 33], s[5 * 33]); o.w = cvt_pk(s[6 * 33], s[7 * 33]);
;         *(u32x4*)(WT + (size_t)(n0dst + n) * ldt + k0 + 8 * c) = o; }
;     asm volatile("s_waitcnt lgkmcnt(0)" ::: "memory"); __builtin_amdgcn_wave_barrier();
	s_waitcnt lgkmcnt(0)
	ds_read2_b32 v[32:33], v7 offset0:33 offset1:41
	ds_read2_b32 v[34:35], v7 offset1:8
	ds_read2_b32 v[36:37], v7 offset0:66 offset1:74
	ds_read2_b32 v[38:39], v7 offset0:99 offset1:107
	ds_read2_b32 v[40:41], v7 offset0:132 offset1:140
	ds_read2_b32 v[42:43], v7 offset0:165 offset1:173
	ds_read2_b32 v[44:45], v7 offset0:198 offset1:206
	ds_read2_b32 v[46:47], v7 offset0:231 offset1:239
	s_lshl_b64 s[2:3], s[2:3], 14
	v_or_b32_e32 v4, s0, v3
	v_lshl_add_u64 v[64:65], v[16:17], 0, s[2:3]
	v_lshlrev_b32_e32 v4, 7, v4
	s_waitcnt lgkmcnt(6)
	v_cvt_pk_bf16_f32 v28, v34, v32
	s_waitcnt lgkmcnt(4)
	v_cvt_pk_bf16_f32 v29, v36, v38
	s_waitcnt lgkmcnt(2)
	v_cvt_pk_bf16_f32 v30, v40, v42
	s_waitcnt lgkmcnt(0)
	v_cvt_pk_bf16_f32 v31, v44, v46
	v_lshl_add_u64 v[66:67], v[64:65], 0, v[4:5]
	global_store_dwordx4 v[66:67], v[28:31], off
	v_or_b32_e32 v4, s0, v9
	v_lshlrev_b32_e32 v4, 7, v4
	v_cvt_pk_bf16_f32 v28, v35, v33
	v_cvt_pk_bf16_f32 v29, v37, v39
	v_cvt_pk_bf16_f32 v30, v41, v43
	v_cvt_pk_bf16_f32 v31, v45, v47
	ds_read2_b32 v[34:35], v7 offset0:49 offset1:57
	ds_read2_b32 v[36:37], v7 offset0:16 offset1:24
	ds_read2_b32 v[38:39], v7 offset0:82 offset1:90
	ds_read2_b32 v[40:41], v7 offset0:115 offset1:123
	ds_read2_b32 v[42:43], v7 offset0:148 offset1:156
	ds_read2_b32 v[44:45], v7 offset0:181 offset1:189
	ds_read2_b32 v[46:47], v7 offset0:214 offset1:222
	ds_read2_b32 v[66:67], v7 offset0:247 offset1:255
	v_lshl_add_u64 v[32:33], v[64:65], 0, v[4:5]
	v_or_b32_e32 v4, s0, v11
	v_lshlrev_b32_e32 v4, 7, v4
	global_store_dwordx4 v[32:33], v[28:31], off
	v_lshl_add_u64 v[32:33], v[64:65], 0, v[4:5]
	v_or_b32_e32 v4, s0, v13
	s_waitcnt lgkmcnt(6)
	v_cvt_pk_bf16_f32 v28, v36, v34
	s_waitcnt lgkmcnt(4)
	v_cvt_pk_bf16_f32 v29, v38, v40
	s_waitcnt lgkmcnt(2)
	v_cvt_pk_bf16_f32 v30, v42, v44
	s_waitcnt lgkmcnt(0)
	v_cvt_pk_bf16_f32 v31, v46, v66
	v_lshlrev_b32_e32 v4, 7, v4
	global_store_dwordx4 v[32:33], v[28:31], off
	v_lshl_add_u64 v[32:33], v[64:65], 0, v[4:5]
	v_readlane_b32 s40, v254, 34
	v_cvt_pk_bf16_f32 v28, v37, v35
	v_cvt_pk_bf16_f32 v29, v39, v41
	v_cvt_pk_bf16_f32 v30, v43, v45
	v_cvt_pk_bf16_f32 v31, v47, v67
	global_store_dwordx4 v[32:33], v[28:31], off
	s_waitcnt lgkmcnt(0)
	s_mov_b64 s[2:3], 0
	v_readlane_b32 s41, v254, 35
	v_readlane_b32 s42, v254, 36
	v_readlane_b32 s43, v254, 37
	v_readlane_b32 s44, v254, 38
	v_readlane_b32 s45, v254, 39
	v_readlane_b32 s46, v254, 40
	v_readlane_b32 s47, v254, 41
	v_readlane_b32 s48, v254, 42
	v_readlane_b32 s49, v254, 43
	v_readlane_b32 s50, v254, 44
	v_readlane_b32 s51, v254, 45
	v_readlane_b32 s52, v254, 46
	v_readlane_b32 s53, v254, 47
	v_readlane_b32 s54, v254, 48
	v_readlane_b32 s55, v254, 49

; __device__ __forceinline__ void transpose_item(const float* __restrict__ W, int ld_src, int k0, int n0src, const float* __restrict__ kscale, bf16_t* __restrict__ WT, int ldt, int n0dst, LAS float* scr, int lane) {
; #pragma unroll 8
;     for (int i = 0; i < 32; ++i) { const int kk = 2 * i + (lane >> 5); float v = W[(size_t)(k0 + kk) * ld_src + n0src + (lane & 31)]; if (kscale) v *= kscale[k0 + kk]; scr[kk * 33 + (lane & 31)] = v; }
; __global__ void __launch_bounds__(512, 2) mk_fwd(Args args) {
;     ...
;             if (r < I_OUT) { const int kb = r / 64, nb = r % 64;
;                 transpose_item(w_out + (size_t)L * DM * DM, DM, kb * 64, nb * 32, nullptr, WOUT + (size_t)L * DM * DM, DM, nb * 32, scr, lane); continue; } r -= I_OUT;
.LBB0_19:
	s_lshl_b32 s39, s13, 1
	s_lshl_b32 s40, s37, 1
	v_or_b32_e32 v4, s39, v1
	v_or_b32_e32 v27, s40, v2
	s_add_i32 s41, s39, 4
	s_add_i32 s42, s40, 4
	s_add_i32 s43, s39, 8
	s_add_i32 s44, s40, 8
	s_add_i32 s45, s39, 12
	s_add_i32 s46, s40, 12
	s_add_i32 s47, s39, 16
	s_add_i32 s48, s40, 16
	s_add_i32 s49, s39, 20
	s_add_i32 s50, s40, 20
	s_add_i32 s51, s39, 24
	s_add_i32 s52, s40, 24
	s_add_i32 s39, s39, 28
	s_add_i32 s40, s40, 28
	v_add_u32_e32 v32, s2, v27
	v_or_b32_e32 v63, s41, v1
	v_or_b32_e32 v78, s42, v2
	v_or_b32_e32 v79, s43, v1
	v_or_b32_e32 v80, s44, v2
	v_or_b32_e32 v81, s45, v1
	v_or_b32_e32 v82, s46, v2
	v_or_b32_e32 v83, s47, v1
	v_or_b32_e32 v84, s48, v2
	v_or_b32_e32 v85, s49, v1
	v_or_b32_e32 v86, s50, v2
	v_or_b32_e32 v87, s51, v1
	v_or_b32_e32 v88, s52, v2
	v_or_b32_e32 v89, s39, v1
	v_or_b32_e32 v90, s40, v2
	v_add_u32_e32 v30, s3, v4
	v_ashrrev_i32_e32 v33, 31, v32
	v_add_u32_e32 v34, s3, v63
	v_add_u32_e32 v36, s2, v78
	v_add_u32_e32 v38, s3, v79
	v_add_u32_e32 v40, s2, v80
	v_add_u32_e32 v42, s3, v81
	v_add_u32_e32 v44, s2, v82
	v_add_u32_e32 v46, s3, v83
	v_add_u32_e32 v64, s2, v84
	v_add_u32_e32 v66, s3, v85
	v_add_u32_e32 v68, s2, v86
	v_add_u32_e32 v70, s3, v87
	v_add_u32_e32 v72, s2, v88
	v_add_u32_e32 v74, s3, v89
	v_add_u32_e32 v76, s2, v90
	v_ashrrev_i32_e32 v31, 31, v30
	v_lshlrev_b64 v[32:33], 13, v[32:33]
	v_ashrrev_i32_e32 v37, 31, v36
	v_ashrrev_i32_e32 v35, 31, v34
	v_ashrrev_i32_e32 v41, 31, v40
	v_ashrrev_i32_e32 v39, 31, v38
	v_ashrrev_i32_e32 v45, 31, v44
	v_ashrrev_i32_e32 v43, 31, v42
	v_ashrrev_i32_e32 v65, 31, v64
	v_ashrrev_i32_e32 v47, 31, v46
	v_ashrrev_i32_e32 v69, 31, v68
	v_ashrrev_i32_e32 v67, 31, v66
	v_ashrrev_i32_e32 v73, 31, v72
	v_ashrrev_i32_e32 v71, 31, v70
	v_ashrrev_i32_e32 v77, 31, v76
	v_ashrrev_i32_e32 v75, 31, v74
	v_lshlrev_b64 v[30:31], 13, v[30:31]
	v_lshl_add_u64 v[32:33], v[28:29], 0, v[32:33]
	v_lshlrev_b64 v[34:35], 13, v[34:35]
	v_lshlrev_b64 v[36:37], 13, v[36:37]
	v_lshlrev_b64 v[38:39], 13, v[38:39]
	v_lshlrev_b64 v[40:41], 13, v[40:41]
	v_lshlrev_b64 v[42:43], 13, v[42:43]
	v_lshlrev_b64 v[44:45], 13, v[44:45]
	v_lshlrev_b64 v[46:47], 13, v[46:47]
	v_lshlrev_b64 v[64:65], 13, v[64:65]
	v_lshlrev_b64 v[66:67], 13, v[66:67]
	v_lshlrev_b64 v[68:69], 13, v[68:69]
	v_lshlrev_b64 v[70:71], 13, v[70:71]
	v_lshlrev_b64 v[72:73], 13, v[72:73]
	v_lshlrev_b64 v[74:75], 13, v[74:75]
	v_lshlrev_b64 v[76:77], 13, v[76:77]
	v_lshl_add_u64 v[30:31], v[28:29], 0, v[30:31]
	v_lshl_add_u64 v[36:37], v[28:29], 0, v[36:37]
	v_lshl_add_u64 v[34:35], v[28:29], 0, v[34:35]
	v_lshl_add_u64 v[40:41], v[28:29], 0, v[40:41]
	v_lshl_add_u64 v[38:39], v[28:29], 0, v[38:39]
	v_lshl_add_u64 v[44:45], v[28:29], 0, v[44:45]
	v_lshl_add_u64 v[42:43], v[28:29], 0, v[42:43]
	v_lshl_add_u64 v[64:65], v[28:29], 0, v[64:65]
	v_lshl_add_u64 v[46:47], v[28:29], 0, v[46:47]
	v_lshl_add_u64 v[68:69], v[28:29], 0, v[68:69]
	v_lshl_add_u64 v[66:67], v[28:29], 0, v[66:67]
	v_lshl_add_u64 v[72:73], v[28:29], 0, v[72:73]
	v_lshl_add_u64 v[70:71], v[28:29], 0, v[70:71]
	v_lshl_add_u64 v[76:77], v[28:29], 0, v[76:77]
	v_lshl_add_u64 v[74:75], v[28:29], 0, v[74:75]
	global_load_dword v91, v[32:33], off nt
	global_load_dword v92, v[30:31], off nt
	global_load_dword v93, v[36:37], off nt
	global_load_dword v94, v[34:35], off nt
	global_load_dword v95, v[40:41], off nt
	global_load_dword v96, v[38:39], off nt
	global_load_dword v97, v[44:45], off nt
	global_load_dword v98, v[42:43], off nt
	global_load_dword v99, v[64:65], off nt
	global_load_dword v100, v[46:47], off nt
	global_load_dword v101, v[68:69], off nt
	global_load_dword v102, v[66:67], off nt
	global_load_dword v103, v[72:73], off nt
	global_load_dword v104, v[70:71], off nt
	global_load_dword v105, v[76:77], off nt
	global_load_dword v106, v[74:75], off nt
	s_add_i32 s37, s37, 16
	s_add_i32 s13, s13, 16
	s_add_i32 s38, s38, -16
	v_mad_u64_u32 v[30:31], s[40:41], v27, s18, v[12:13]
	s_cmp_lg_u32 s38, 0
	v_mad_u64_u32 v[32:33], s[40:41], v4, s18, v[12:13]
	v_mad_u64_u32 v[34:35], s[40:41], v78, s18, v[12:13]
	v_mad_u64_u32 v[36:37], s[40:41], v63, s18, v[12:13]
	v_mad_u64_u32 v[38:39], s[40:41], v80, s18, v[12:13]
	v_mad_u64_u32 v[40:41], s[40:41], v79, s18, v[12:13]
	v_mad_u64_u32 v[42:43], s[40:41], v82, s18, v[12:13]
	v_mad_u64_u32 v[44:45], s[40:41], v81, s18, v[12:13]
	v_mad_u64_u32 v[46:47], s[40:41], v84, s18, v[12:13]
	v_mad_u64_u32 v[64:65], s[40:41], v83, s18, v[12:13]
	v_mad_u64_u32 v[66:67], s[40:41], v86, s18, v[12:13]
	v_mad_u64_u32 v[68:69], s[40:41], v85, s18, v[12:13]
	v_mad_u64_u32 v[70:71], s[40:41], v88, s18, v[12:13]
	v_mad_u64_u32 v[72:73], s[40:41], v87, s18, v[12:13]
	v_mad_u64_u32 v[74:75], s[40:41], v90, s18, v[12:13]
	v_mad_u64_u32 v[76:77], s[40:41], v89, s18, v[12:13]
	s_waitcnt vmcnt(15)
	ds_write_b32 v30, v91
	s_waitcnt vmcnt(14)
	ds_write_b32 v32, v92
	s_waitcnt vmcnt(13)
	ds_write_b32 v34, v93
	s_waitcnt vmcnt(12)
	ds_write_b32 v36, v94
	s_waitcnt vmcnt(11)
	ds_write_b32 v38, v95
	s_waitcnt vmcnt(10)
	ds_write_b32 v40, v96
	s_waitcnt vmcnt(9)
	ds_write_b32 v42, v97
	s_waitcnt vmcnt(8)
	ds_write_b32 v44, v98
	s_waitcnt vmcnt(7)
	ds_write_b32 v46, v99
	s_waitcnt vmcnt(6)
	ds_write_b32 v64, v100
	s_waitcnt vmcnt(5)
	ds_write_b32 v66, v101
	s_waitcnt vmcnt(4)
	ds_write_b32 v68, v102
	s_waitcnt vmcnt(3)
	ds_write_b32 v70, v103
	s_waitcnt vmcnt(2)
	ds_write_b32 v72, v104
	s_waitcnt vmcnt(1)
	ds_write_b32 v74, v105
	s_waitcnt vmcnt(0)
	ds_write_b32 v76, v106
	s_cbranch_scc1 .LBB0_19
; #define LAS __attribute__((address_space(3)))
; __device__ __forceinline__ unsigned cvt_pk(float lo, float hi) { f32x2_t v = {lo, hi}; bf16x2_t b = __builtin_convertvector(v, bf16x2_t); return __builtin_bit_cast(unsigned, b); }
; __device__ __forceinline__ void transpose_item(const float* __restrict__ W, int ld_src, int k0, int n0src, const float* __restrict__ kscale, bf16_t* __restrict__ WT, int ldt, int n0dst, LAS float* scr, int lane) {
;     ...
;     asm volatile("s_waitcnt lgkmcnt(0)" ::: "memory"); __builtin_amdgcn_wave_barrier();
;     const int c = lane & 7;
; #pragma unroll
;     for (int jn = 0; jn < 4; ++jn) { const int n = (lane >> 3) + 8 * jn; const LAS float* s = scr + (8 * c) * 33 + n;
;         u32x4 o; o.x = cvt_pk(s[0 * 33], s[1 * 33]); o.y = cvt_pk(s[2 * 33], s[3 * 33]); o.z = cvt_pk(s[4 * 33], s[5 * 33]); o.w = cvt_pk(s[6 * 33], s[7 * 33]);
;         *(u32x4*)(WT + (size_t)(n0dst + n) * ldt + k0 + 8 * c) = o; }
;     asm volatile("s_waitcnt lgkmcnt(0)" ::: "memory"); __builtin_amdgcn_wave_barrier();
	s_lshl_b64 s[14:15], s[14:15], 1
	s_add_u32 s13, s19, s14
	s_mov_b32 s3, s1
	s_addc_u32 s14, s23, s15
	s_waitcnt lgkmcnt(0)
	s_lshl_b64 s[2:3], s[2:3], 1
	ds_read2_b32 v[32:33], v7 offset0:33 offset1:41
	ds_read2_b32 v[34:35], v7 offset1:8
	ds_read2_b32 v[36:37], v7 offset0:66 offset1:74
	ds_read2_b32 v[38:39], v7 offset0:99 offset1:107
	ds_read2_b32 v[40:41], v7 offset0:132 offset1:140
	ds_read2_b32 v[42:43], v7 offset0:165 offset1:173
	ds_read2_b32 v[44:45], v7 offset0:198 offset1:206
	ds_read2_b32 v[46:47], v7 offset0:231 offset1:239
	s_add_u32 s2, s13, s2
	s_addc_u32 s3, s14, s3
	v_lshlrev_b32_e32 v4, 1, v14
	v_lshl_add_u64 v[64:65], s[2:3], 0, v[4:5]
	v_or_b32_e32 v4, s0, v3
	v_lshlrev_b32_e32 v4, 12, v4
	s_waitcnt lgkmcnt(6)
	v_cvt_pk_bf16_f32 v28, v34, v32
	s_waitcnt lgkmcnt(4)
	v_cvt_pk_bf16_f32 v29, v36, v38
	s_waitcnt lgkmcnt(2)
	v_cvt_pk_bf16_f32 v30, v40, v42
	s_waitcnt lgkmcnt(0)
	v_cvt_pk_bf16_f32 v31, v44, v46
	v_lshl_add_u64 v[66:67], v[64:65], 0, v[4:5]
	global_store_dwordx4 v[66:67], v[28:31], off
	v_or_b32_e32 v4, s0, v9
	v_lshlrev_b32_e32 v4, 12, v4
	v_cvt_pk_bf16_f32 v28, v35, v33
	v_cvt_pk_bf16_f32 v29, v37, v39
	v_cvt_pk_bf16_f32 v30, v41, v43
	v_cvt_pk_bf16_f32 v31, v45, v47
	ds_read2_b32 v[34:35], v7 offset0:49 offset1:57
	ds_read2_b32 v[36:37], v7 offset0:16 offset1:24
	ds_read2_b32 v[38:39], v7 offset0:82 offset1:90
	ds_read2_b32 v[40:41], v7 offset0:115 offset1:123
	ds_read2_b32 v[42:43], v7 offset0:148 offset1:156
	ds_read2_b32 v[44:45], v7 offset0:181 offset1:189
	ds_read2_b32 v[46:47], v7 offset0:214 offset1:222
	ds_read2_b32 v[66:67], v7 offset0:247 offset1:255
	v_lshl_add_u64 v[32:33], v[64:65], 0, v[4:5]
	v_or_b32_e32 v4, s0, v11
	v_lshlrev_b32_e32 v4, 12, v4
	global_store_dwordx4 v[32:33], v[28:31], off
	v_lshl_add_u64 v[32:33], v[64:65], 0, v[4:5]
	v_or_b32_e32 v4, s0, v13
	s_waitcnt lgkmcnt(6)
	v_cvt_pk_bf16_f32 v28, v36, v34
	s_waitcnt lgkmcnt(4)
	v_cvt_pk_bf16_f32 v29, v38, v40
	s_waitcnt lgkmcnt(2)
	v_cvt_pk_bf16_f32 v30, v42, v44
	s_waitcnt lgkmcnt(0)
	v_cvt_pk_bf16_f32 v31, v46, v66
	v_lshlrev_b32_e32 v4, 12, v4
	global_store_dwordx4 v[32:33], v[28:31], off
	v_lshl_add_u64 v[32:33], v[64:65], 0, v[4:5]
	v_readlane_b32 s40, v254, 34
	v_cvt_pk_bf16_f32 v28, v37, v35
	v_cvt_pk_bf16_f32 v29, v39, v41
	v_cvt_pk_bf16_f32 v30, v43, v45
	v_cvt_pk_bf16_f32 v31, v47, v67
	global_store_dwordx4 v[32:33], v[28:31], off
	s_waitcnt lgkmcnt(0)
	v_readlane_b32 s41, v254, 35
	v_readlane_b32 s42, v254, 36
	v_readlane_b32 s43, v254, 37
	v_readlane_b32 s44, v254, 38
	v_readlane_b32 s45, v254, 39
	v_readlane_b32 s46, v254, 40
	v_readlane_b32 s47, v254, 41
	v_readlane_b32 s48, v254, 42
	v_readlane_b32 s49, v254, 43
	v_readlane_b32 s50, v254, 44
	v_readlane_b32 s51, v254, 45
	v_readlane_b32 s52, v254, 46
	v_readlane_b32 s53, v254, 47
	v_readlane_b32 s54, v254, 48
	v_readlane_b32 s55, v254, 49

; __device__ __forceinline__ void transpose_item(const float* __restrict__ W, int ld_src, int k0, int n0src, const float* __restrict__ kscale, bf16_t* __restrict__ WT, int ldt, int n0dst, LAS float* scr, int lane) {
; #pragma unroll 8
;     for (int i = 0; i < 32; ++i) { const int kk = 2 * i + (lane >> 5); float v = W[(size_t)(k0 + kk) * ld_src + n0src + (lane & 31)]; if (kscale) v *= kscale[k0 + kk]; scr[kk * 33 + (lane & 31)] = v; }
; __global__ void __launch_bounds__(512, 2) mk_fwd(Args args) {
;     ...
;             if (r < I_BR) { const int n3 = r / 1024, rr = r % 1024, kb = rr / 64, nb = rr % 64;
;                 transpose_item(w_branch + ((size_t)L * 3 + n3) * 1024 * 2048, 2048, kb * 64, nb * 32, nullptr, WBR + ((size_t)L * 3 + n3) * 2048 * 1024, 1024, nb * 32, scr, lane); continue; } r -= I_BR;
.LBB0_24:
	s_lshl_b32 s39, s15, 1
	s_lshl_b32 s40, s37, 1
	v_or_b32_e32 v63, s40, v2
	s_add_i32 s41, s39, 4
	s_add_i32 s42, s40, 4
	s_add_i32 s44, s40, 8
	v_add_u32_e32 v4, s13, v63
	v_or_b32_e32 v68, s41, v1
	v_or_b32_e32 v69, s42, v2
	v_mov_b32_e32 v33, v5
	v_or_b32_e32 v27, s39, v1
	s_add_i32 s46, s40, 12
	v_or_b32_e32 v71, s44, v2
	v_lshlrev_b64 v[46:47], 13, v[4:5]
	v_add_u32_e32 v32, s14, v68
	v_add_u32_e32 v4, s13, v69
	v_mov_b32_e32 v31, v5
	s_add_i32 s43, s39, 8
	s_add_i32 s45, s39, 12
	s_add_i32 s48, s40, 16
	v_add_u32_e32 v30, s14, v27
	v_or_b32_e32 v73, s46, v2
	v_lshlrev_b64 v[32:33], 13, v[32:33]
	v_lshlrev_b64 v[64:65], 13, v[4:5]
	v_add_u32_e32 v4, s13, v71
	s_add_i32 s50, s40, 20
	v_or_b32_e32 v70, s43, v1
	v_or_b32_e32 v72, s45, v1
	v_or_b32_e32 v75, s48, v2
	v_lshlrev_b64 v[30:31], 13, v[30:31]
	v_lshl_add_u64 v[46:47], v[28:29], 0, v[46:47]
	v_lshl_add_u64 v[32:33], v[28:29], 0, v[32:33]
	v_lshlrev_b64 v[66:67], 13, v[4:5]
	v_add_u32_e32 v4, s13, v73
	v_mov_b32_e32 v35, v5
	v_mov_b32_e32 v37, v5
	s_add_i32 s47, s39, 16
	s_add_i32 s49, s39, 20
	s_add_i32 s52, s40, 24
	v_or_b32_e32 v77, s50, v2
	v_add_u32_e32 v34, s14, v70
	v_add_u32_e32 v36, s14, v72
	v_lshl_add_u64 v[30:31], v[28:29], 0, v[30:31]
	v_lshl_add_u64 v[64:65], v[28:29], 0, v[64:65]
	global_load_dword v82, v[46:47], off nt
	global_load_dword v83, v[30:31], off nt
	global_load_dword v84, v[64:65], off nt
	global_load_dword v85, v[32:33], off nt
	v_lshlrev_b64 v[32:33], 13, v[4:5]
	v_add_u32_e32 v4, s13, v75
	s_add_i32 s51, s39, 24
	s_add_i32 s39, s39, 28
	s_add_i32 s40, s40, 28
	v_or_b32_e32 v74, s47, v1
	v_or_b32_e32 v76, s49, v1
	v_or_b32_e32 v79, s52, v2
	v_lshlrev_b64 v[34:35], 13, v[34:35]
	v_lshlrev_b64 v[36:37], 13, v[36:37]
	v_lshl_add_u64 v[30:31], v[28:29], 0, v[66:67]
	v_lshl_add_u64 v[32:33], v[28:29], 0, v[32:33]
	v_lshlrev_b64 v[46:47], 13, v[4:5]
	v_add_u32_e32 v4, s13, v77
	v_mov_b32_e32 v39, v5
	v_mov_b32_e32 v41, v5
	v_or_b32_e32 v78, s51, v1
	v_or_b32_e32 v80, s39, v1
	v_or_b32_e32 v81, s40, v2
	v_add_u32_e32 v38, s14, v74
	v_add_u32_e32 v40, s14, v76
	v_lshl_add_u64 v[34:35], v[28:29], 0, v[34:35]
	v_lshl_add_u64 v[36:37], v[28:29], 0, v[36:37]
	global_load_dword v86, v[30:31], off nt
	global_load_dword v87, v[34:35], off nt
	global_load_dword v88, v[32:33], off nt
	global_load_dword v89, v[36:37], off nt
	v_lshlrev_b64 v[32:33], 13, v[4:5]
	v_add_u32_e32 v4, s13, v79
	v_mov_b32_e32 v43, v5
	v_mov_b32_e32 v45, v5
	v_add_u32_e32 v42, s14, v78
	v_add_u32_e32 v44, s14, v80
	v_lshlrev_b64 v[38:39], 13, v[38:39]
	v_lshlrev_b64 v[40:41], 13, v[40:41]
	v_lshl_add_u64 v[30:31], v[28:29], 0, v[46:47]
	v_lshl_add_u64 v[32:33], v[28:29], 0, v[32:33]
	v_lshlrev_b64 v[34:35], 13, v[4:5]
	v_add_u32_e32 v4, s13, v81
	v_lshlrev_b64 v[42:43], 13, v[42:43]
	v_lshlrev_b64 v[44:45], 13, v[44:45]
	v_lshl_add_u64 v[38:39], v[28:29], 0, v[38:39]
	v_lshl_add_u64 v[40:41], v[28:29], 0, v[40:41]
	global_load_dword v90, v[30:31], off nt
	global_load_dword v91, v[38:39], off nt
	global_load_dword v92, v[32:33], off nt
	global_load_dword v93, v[40:41], off nt
	v_lshl_add_u64 v[30:31], v[28:29], 0, v[34:35]
	v_lshlrev_b64 v[32:33], 13, v[4:5]
	v_lshl_add_u64 v[42:43], v[28:29], 0, v[42:43]
	v_lshl_add_u64 v[44:45], v[28:29], 0, v[44:45]
	v_lshl_add_u64 v[32:33], v[28:29], 0, v[32:33]
	global_load_dword v4, v[30:31], off nt
	global_load_dword v94, v[42:43], off nt
	global_load_dword v95, v[32:33], off nt
	global_load_dword v96, v[44:45], off nt
	s_add_i32 s37, s37, 16
	s_add_i32 s15, s15, 16
	s_add_i32 s38, s38, -16
	v_mad_u64_u32 v[30:31], s[40:41], v63, s18, v[12:13]
	s_cmp_lg_u32 s38, 0
	v_mad_u64_u32 v[32:33], s[40:41], v27, s18, v[12:13]
	v_mad_u64_u32 v[34:35], s[40:41], v69, s18, v[12:13]
	v_mad_u64_u32 v[36:37], s[40:41], v68, s18, v[12:13]
	v_mad_u64_u32 v[38:39], s[40:41], v71, s18, v[12:13]
	v_mad_u64_u32 v[40:41], s[40:41], v70, s18, v[12:13]
	v_mad_u64_u32 v[42:43], s[40:41], v73, s18, v[12:13]
	v_mad_u64_u32 v[44:45], s[40:41], v72, s18, v[12:13]
	v_mad_u64_u32 v[46:47], s[40:41], v75, s18, v[12:13]
	v_mad_u64_u32 v[64:65], s[40:41], v74, s18, v[12:13]
	v_mad_u64_u32 v[66:67], s[40:41], v77, s18, v[12:13]
	v_mad_u64_u32 v[68:69], s[40:41], v76, s18, v[12:13]
	v_mad_u64_u32 v[70:71], s[40:41], v79, s18, v[12:13]
	v_mad_u64_u32 v[72:73], s[40:41], v78, s18, v[12:13]
	v_mad_u64_u32 v[74:75], s[40:41], v81, s18, v[12:13]
	v_mad_u64_u32 v[76:77], s[40:41], v80, s18, v[12:13]
	s_waitcnt vmcnt(15)
	ds_write_b32 v30, v82
	s_waitcnt vmcnt(14)
	ds_write_b32 v32, v83
	s_waitcnt vmcnt(13)
	ds_write_b32 v34, v84
	s_waitcnt vmcnt(12)
	ds_write_b32 v36, v85
	s_waitcnt vmcnt(11)
	ds_write_b32 v38, v86
	s_waitcnt vmcnt(10)
	ds_write_b32 v40, v87
	s_waitcnt vmcnt(9)
	ds_write_b32 v42, v88
	s_waitcnt vmcnt(8)
	ds_write_b32 v44, v89
	s_waitcnt vmcnt(7)
	ds_write_b32 v46, v90
	s_waitcnt vmcnt(6)
	ds_write_b32 v64, v91
	s_waitcnt vmcnt(5)
	ds_write_b32 v66, v92
	s_waitcnt vmcnt(4)
	ds_write_b32 v68, v93
	s_waitcnt vmcnt(3)
	ds_write_b32 v70, v4
	s_waitcnt vmcnt(2)
	ds_write_b32 v72, v94
	s_waitcnt vmcnt(1)
	ds_write_b32 v74, v95
	s_waitcnt vmcnt(0)
	ds_write_b32 v76, v96
	s_cbranch_scc1 .LBB0_24
; #define LAS __attribute__((address_space(3)))
; __device__ __forceinline__ unsigned cvt_pk(float lo, float hi) { f32x2_t v = {lo, hi}; bf16x2_t b = __builtin_convertvector(v, bf16x2_t); return __builtin_bit_cast(unsigned, b); }
; __device__ __forceinline__ void transpose_item(const float* __restrict__ W, int ld_src, int k0, int n0src, const float* __restrict__ kscale, bf16_t* __restrict__ WT, int ldt, int n0dst, LAS float* scr, int lane) {
;     ...
;     asm volatile("s_waitcnt lgkmcnt(0)" ::: "memory"); __builtin_amdgcn_wave_barrier();
;     const int c = lane & 7;
; #pragma unroll
;     for (int jn = 0; jn < 4; ++jn) { const int n = (lane >> 3) + 8 * jn; const LAS float* s = scr + (8 * c) * 33 + n;
;         u32x4 o; o.x = cvt_pk(s[0 * 33], s[1 * 33]); o.y = cvt_pk(s[2 * 33], s[3 * 33]); o.z = cvt_pk(s[4 * 33], s[5 * 33]); o.w = cvt_pk(s[6 * 33], s[7 * 33]);
;         *(u32x4*)(WT + (size_t)(n0dst + n) * ldt + k0 + 8 * c) = o; }
;     asm volatile("s_waitcnt lgkmcnt(0)" ::: "memory"); __builtin_amdgcn_wave_barrier();
	s_lshl_b64 s[2:3], s[2:3], 22
	s_add_u32 s2, s24, s2
	s_addc_u32 s3, s25, s3
	s_waitcnt lgkmcnt(0)
	s_lshl_b32 s13, s13, 1
	ds_read2_b32 v[32:33], v7 offset0:33 offset1:41
	ds_read2_b32 v[34:35], v7 offset1:8
	ds_read2_b32 v[36:37], v7 offset0:66 offset1:74
	ds_read2_b32 v[38:39], v7 offset0:99 offset1:107
	ds_read2_b32 v[40:41], v7 offset0:132 offset1:140
	ds_read2_b32 v[42:43], v7 offset0:165 offset1:173
	ds_read2_b32 v[44:45], v7 offset0:198 offset1:206
	ds_read2_b32 v[46:47], v7 offset0:231 offset1:239
	s_add_u32 s2, s2, s13
	s_addc_u32 s3, s3, 0
	v_lshlrev_b32_e32 v4, 1, v14
	v_lshl_add_u64 v[64:65], s[2:3], 0, v[4:5]
	v_or_b32_e32 v4, s0, v3
	v_lshlrev_b32_e32 v4, 11, v4
	s_waitcnt lgkmcnt(6)
	v_cvt_pk_bf16_f32 v28, v34, v32
	s_waitcnt lgkmcnt(4)
	v_cvt_pk_bf16_f32 v29, v36, v38
	s_waitcnt lgkmcnt(2)
	v_cvt_pk_bf16_f32 v30, v40, v42
	s_waitcnt lgkmcnt(0)
	v_cvt_pk_bf16_f32 v31, v44, v46
	v_lshl_add_u64 v[66:67], v[64:65], 0, v[4:5]
	global_store_dwordx4 v[66:67], v[28:31], off
	v_or_b32_e32 v4, s0, v9
	v_lshlrev_b32_e32 v4, 11, v4
	v_cvt_pk_bf16_f32 v28, v35, v33
	v_cvt_pk_bf16_f32 v29, v37, v39
	v_cvt_pk_bf16_f32 v30, v41, v43
	v_cvt_pk_bf16_f32 v31, v45, v47
	ds_read2_b32 v[34:35], v7 offset0:49 offset1:57
	ds_read2_b32 v[36:37], v7 offset0:16 offset1:24
	ds_read2_b32 v[38:39], v7 offset0:82 offset1:90
	ds_read2_b32 v[40:41], v7 offset0:115 offset1:123
	ds_read2_b32 v[42:43], v7 offset0:148 offset1:156
	ds_read2_b32 v[44:45], v7 offset0:181 offset1:189
	ds_read2_b32 v[46:47], v7 offset0:214 offset1:222
	ds_read2_b32 v[66:67], v7 offset0:247 offset1:255
	v_lshl_add_u64 v[32:33], v[64:65], 0, v[4:5]
	v_or_b32_e32 v4, s0, v11
	v_lshlrev_b32_e32 v4, 11, v4
	global_store_dwordx4 v[32:33], v[28:31], off
	v_lshl_add_u64 v[32:33], v[64:65], 0, v[4:5]
	v_or_b32_e32 v4, s0, v13
	s_waitcnt lgkmcnt(6)
	v_cvt_pk_bf16_f32 v28, v36, v34
	s_waitcnt lgkmcnt(4)
	v_cvt_pk_bf16_f32 v29, v38, v40
	s_waitcnt lgkmcnt(2)
	v_cvt_pk_bf16_f32 v30, v42, v44
	s_waitcnt lgkmcnt(0)
	v_cvt_pk_bf16_f32 v31, v46, v66
	v_lshlrev_b32_e32 v4, 11, v4
	global_store_dwordx4 v[32:33], v[28:31], off
	v_lshl_add_u64 v[32:33], v[64:65], 0, v[4:5]
	v_readlane_b32 s40, v254, 34
	v_cvt_pk_bf16_f32 v28, v37, v35
	v_cvt_pk_bf16_f32 v29, v39, v41
	v_cvt_pk_bf16_f32 v30, v43, v45
	v_cvt_pk_bf16_f32 v31, v47, v67
	global_store_dwordx4 v[32:33], v[28:31], off
	s_waitcnt lgkmcnt(0)
	v_readlane_b32 s41, v254, 35
	v_readlane_b32 s42, v254, 36
	v_readlane_b32 s43, v254, 37
	v_readlane_b32 s44, v254, 38
	v_readlane_b32 s45, v254, 39
	v_readlane_b32 s46, v254, 40
	v_readlane_b32 s47, v254, 41
	v_readlane_b32 s48, v254, 42
	v_readlane_b32 s49, v254, 43
	v_readlane_b32 s50, v254, 44
	v_readlane_b32 s51, v254, 45
	v_readlane_b32 s52, v254, 46
	v_readlane_b32 s53, v254, 47
	v_readlane_b32 s54, v254, 48
	v_readlane_b32 s55, v254, 49

; __device__ __forceinline__ void transpose_item(const float* __restrict__ W, int ld_src, int k0, int n0src, const float* __restrict__ kscale, bf16_t* __restrict__ WT, int ldt, int n0dst, LAS float* scr, int lane) {
;     ...
;     for (int i = 0; i < 32; ++i) { const int kk = 2 * i + (lane >> 5); float v = W[(size_t)(k0 + kk) * ld_src + n0src + (lane & 31)]; if (kscale) v *= kscale[k0 + kk]; scr[kk * 33 + (lane & 31)] = v; }
; __global__ void __launch_bounds__(512, 2) mk_fwd(Args args) {
;     ...
;             if (r < I_UQ) { const int kb = r / 48, nb = r % 48;
;                 transpose_item(w_uq + (size_t)L * 512 * 1536, 1536, kb * 64, nb * 32, qng + L * 512, WUQ + (size_t)L * 1536 * 512, 512, nb * 32, scr, lane); continue; } r -= I_UQ;
;             if (r < I_UKV) { const int kb = r / 64, nb = r % 64;
;                 transpose_item(w_ukv + (size_t)L * 256 * 2048, 2048, kb * 64, nb * 32, kvng + L * 256, WUKV + (size_t)L * 2048 * 256, 256, nb * 32, scr, lane); continue; } r -= I_UKV;
.LBB0_30:
	v_lshl_add_u64 v[64:65], v[34:35], 0, s[14:15]
	global_load_dword v27, v[64:65], off nt
	v_cndmask_b32_e64 v63, 0, 1, s[4:5]
	v_cmp_ne_u32_e64 s[2:3], 1, v63
	s_andn2_b64 vcc, exec, s[4:5]
	s_cbranch_vccnz .LBB0_32
	global_load_dword v63, v[30:31], off nt
	s_waitcnt vmcnt(0)
	v_mul_f32_e32 v27, v27, v63
.LBB0_32:
	v_lshl_add_u64 v[64:65], v[38:39], 0, s[14:15]
	global_load_dword v63, v[64:65], off nt
	s_and_b64 vcc, exec, s[2:3]
	s_waitcnt vmcnt(1)
	ds_write_b32 v4, v27
	s_cbranch_vccnz .LBB0_34
	global_load_dword v27, v[42:43], off offset:-24 nt
	s_waitcnt vmcnt(0)
	v_mul_f32_e32 v63, v63, v27
.LBB0_34:
	v_lshl_add_u64 v[64:65], v[46:47], 0, s[14:15]
	global_load_dword v27, v[64:65], off nt
	s_and_b64 vcc, exec, s[2:3]
	s_waitcnt vmcnt(1)
	ds_write_b32 v4, v63 offset:264
	s_cbranch_vccnz .LBB0_36
	global_load_dword v63, v[42:43], off offset:-16 nt
	s_waitcnt vmcnt(0)
	v_mul_f32_e32 v27, v27, v63
.LBB0_36:
	v_lshl_add_u64 v[64:65], v[44:45], 0, s[14:15]
	global_load_dword v63, v[64:65], off nt
	s_and_b64 vcc, exec, s[2:3]
	s_waitcnt vmcnt(1)
	ds_write_b32 v4, v27 offset:528
	s_cbranch_vccnz .LBB0_38
	global_load_dword v27, v[42:43], off offset:-8 nt
	s_waitcnt vmcnt(0)
	v_mul_f32_e32 v63, v63, v27
.LBB0_38:
	v_lshl_add_u64 v[64:65], v[40:41], 0, s[14:15]
	global_load_dword v27, v[64:65], off nt
	s_and_b64 vcc, exec, s[2:3]
	s_waitcnt vmcnt(1)
	ds_write_b32 v4, v63 offset:792
	s_cbranch_vccnz .LBB0_40
	global_load_dword v63, v[42:43], off nt
	s_waitcnt vmcnt(0)
	v_mul_f32_e32 v27, v27, v63
.LBB0_40:
	v_lshl_add_u64 v[64:65], v[36:37], 0, s[14:15]
	global_load_dword v63, v[64:65], off nt
	s_and_b64 vcc, exec, s[2:3]
	s_waitcnt vmcnt(1)
	ds_write_b32 v4, v27 offset:1056
	s_cbranch_vccnz .LBB0_42
	global_load_dword v27, v[42:43], off offset:8 nt
	s_waitcnt vmcnt(0)
	v_mul_f32_e32 v63, v63, v27
.LBB0_42:
	v_lshl_add_u64 v[64:65], v[32:33], 0, s[14:15]
	global_load_dword v27, v[64:65], off nt
	s_and_b64 vcc, exec, s[2:3]
	s_waitcnt vmcnt(1)
	ds_write_b32 v4, v63 offset:1320
	s_cbranch_vccnz .LBB0_44
	global_load_dword v63, v[42:43], off offset:16 nt
	s_waitcnt vmcnt(0)
	v_mul_f32_e32 v27, v27, v63
.LBB0_44:
	v_lshl_add_u64 v[64:65], v[28:29], 0, s[14:15]
	global_load_dword v63, v[64:65], off nt
	s_and_b64 vcc, exec, s[2:3]
	s_waitcnt vmcnt(1)
	ds_write_b32 v4, v27 offset:1584
	s_cbranch_vccnz .LBB0_29
	global_load_dword v27, v[42:43], off offset:24 nt
	s_waitcnt vmcnt(0)
	v_mul_f32_e32 v63, v63, v27
	s_branch .LBB0_29

; __device__ __forceinline__ void transpose_item(const float* __restrict__ W, int ld_src, int k0, int n0src, const float* __restrict__ kscale, bf16_t* __restrict__ WT, int ldt, int n0dst, LAS float* scr, int lane) {
;     ...
;     for (int i = 0; i < 32; ++i) { const int kk = 2 * i + (lane >> 5); float v = W[(size_t)(k0 + kk) * ld_src + n0src + (lane & 31)]; if (kscale) v *= kscale[k0 + kk]; scr[kk * 33 + (lane & 31)] = v; }
; __global__ void __launch_bounds__(512, 2) mk_fwd(Args args) {
;     ...
;             if (r < I_UQ) { const int kb = r / 48, nb = r % 48;
;                 transpose_item(w_uq + (size_t)L * 512 * 1536, 1536, kb * 64, nb * 32, qng + L * 512, WUQ + (size_t)L * 1536 * 512, 512, nb * 32, scr, lane); continue; } r -= I_UQ;
;             if (r < I_UKV) { const int kb = r / 64, nb = r % 64;
;                 transpose_item(w_ukv + (size_t)L * 256 * 2048, 2048, kb * 64, nb * 32, kvng + L * 256, WUKV + (size_t)L * 2048 * 256, 256, nb * 32, scr, lane); continue; } r -= I_UKV;
.LBB0_51:
	v_lshl_add_u64 v[46:47], v[30:31], 0, s[14:15]
	global_load_dword v27, v[46:47], off nt
	v_cndmask_b32_e64 v46, 0, 1, s[10:11]
	v_cmp_ne_u32_e64 s[2:3], 1, v46
	s_andn2_b64 vcc, exec, s[10:11]
	s_cbranch_vccnz .LBB0_53
	global_load_dword v46, v[34:35], off offset:-56 nt
	s_waitcnt vmcnt(0)
	v_mul_f32_e32 v27, v27, v46
.LBB0_53:
	v_lshl_add_u64 v[46:47], v[44:45], 0, s[14:15]
	global_load_dword v46, v[46:47], off nt
	s_and_b64 vcc, exec, s[2:3]
	s_waitcnt vmcnt(1)
	ds_write_b32 v4, v27
	s_cbranch_vccnz .LBB0_55
	global_load_dword v27, v[34:35], off offset:-48 nt
	s_waitcnt vmcnt(0)
	v_mul_f32_e32 v46, v46, v27
.LBB0_55:
	v_lshl_add_u64 v[64:65], v[42:43], 0, s[14:15]
	global_load_dword v27, v[64:65], off nt
	s_and_b64 vcc, exec, s[2:3]
	s_waitcnt vmcnt(1)
	ds_write_b32 v4, v46 offset:264
	s_cbranch_vccnz .LBB0_57
	global_load_dword v46, v[34:35], off offset:-40 nt
	s_waitcnt vmcnt(0)
	v_mul_f32_e32 v27, v27, v46
.LBB0_57:
	v_lshl_add_u64 v[46:47], v[40:41], 0, s[14:15]
	global_load_dword v46, v[46:47], off nt
	s_and_b64 vcc, exec, s[2:3]
	s_waitcnt vmcnt(1)
	ds_write_b32 v4, v27 offset:528
	s_cbranch_vccnz .LBB0_59
	global_load_dword v27, v[34:35], off offset:-32 nt
	s_waitcnt vmcnt(0)
	v_mul_f32_e32 v46, v46, v27
.LBB0_59:
	v_lshl_add_u64 v[64:65], v[38:39], 0, s[14:15]
	global_load_dword v27, v[64:65], off nt
	s_and_b64 vcc, exec, s[2:3]
	s_waitcnt vmcnt(1)
	ds_write_b32 v4, v46 offset:792
	s_cbranch_vccnz .LBB0_61
	global_load_dword v46, v[34:35], off offset:-24 nt
	s_waitcnt vmcnt(0)
	v_mul_f32_e32 v27, v27, v46
.LBB0_61:
	v_lshl_add_u64 v[46:47], v[36:37], 0, s[14:15]
	global_load_dword v46, v[46:47], off nt
	s_and_b64 vcc, exec, s[2:3]
	s_waitcnt vmcnt(1)
	ds_write_b32 v4, v27 offset:1056
	s_cbranch_vccnz .LBB0_63
	global_load_dword v27, v[34:35], off offset:-16 nt
	s_waitcnt vmcnt(0)
	v_mul_f32_e32 v46, v46, v27
.LBB0_63:
	v_lshl_add_u64 v[64:65], v[32:33], 0, s[14:15]
	global_load_dword v27, v[64:65], off nt
	s_and_b64 vcc, exec, s[2:3]
	s_waitcnt vmcnt(1)
	ds_write_b32 v4, v46 offset:1320
	s_cbranch_vccnz .LBB0_65
	global_load_dword v46, v[34:35], off offset:-8 nt
	s_waitcnt vmcnt(0)
	v_mul_f32_e32 v27, v27, v46
.LBB0_65:
	v_lshl_add_u64 v[46:47], v[28:29], 0, s[14:15]
	global_load_dword v46, v[46:47], off nt
	s_and_b64 vcc, exec, s[2:3]
	s_waitcnt vmcnt(1)
	ds_write_b32 v4, v27 offset:1584
	s_cbranch_vccnz .LBB0_50
	global_load_dword v27, v[34:35], off nt
	s_waitcnt vmcnt(0)
	v_mul_f32_e32 v46, v46, v27
	s_branch .LBB0_50

; __device__ __forceinline__ void transpose_item(const float* __restrict__ W, int ld_src, int k0, int n0src, const float* __restrict__ kscale, bf16_t* __restrict__ WT, int ldt, int n0dst, LAS float* scr, int lane) {
; #pragma unroll 8
;     for (int i = 0; i < 32; ++i) { const int kk = 2 * i + (lane >> 5); float v = W[(size_t)(k0 + kk) * ld_src + n0src + (lane & 31)]; if (kscale) v *= kscale[k0 + kk]; scr[kk * 33 + (lane & 31)] = v; }
.LBB0_70:
	s_lshl_b32 s37, s13, 1
	s_lshl_b32 s38, s15, 1
	v_or_b32_e32 v4, s37, v1
	v_or_b32_e32 v27, s38, v2
	s_add_i32 s39, s37, 4
	s_add_i32 s40, s38, 4
	s_add_i32 s41, s37, 8
	s_add_i32 s42, s38, 8
	s_add_i32 s43, s37, 12
	s_add_i32 s44, s38, 12
	s_add_i32 s45, s37, 16
	s_add_i32 s46, s38, 16
	s_add_i32 s47, s37, 20
	s_add_i32 s48, s38, 20
	s_add_i32 s49, s37, 24
	s_add_i32 s50, s38, 24
	s_add_i32 s37, s37, 28
	s_add_i32 s38, s38, 28
	v_add_u32_e32 v30, s14, v27
	v_or_b32_e32 v63, s39, v1
	v_or_b32_e32 v78, s40, v2
	v_or_b32_e32 v79, s41, v1
	v_or_b32_e32 v80, s42, v2
	v_or_b32_e32 v81, s43, v1
	v_or_b32_e32 v82, s44, v2
	v_or_b32_e32 v83, s45, v1
	v_or_b32_e32 v84, s46, v2
	v_or_b32_e32 v85, s47, v1
	v_or_b32_e32 v86, s48, v2
	v_or_b32_e32 v87, s49, v1
	v_or_b32_e32 v88, s50, v2
	v_or_b32_e32 v89, s37, v1
	v_or_b32_e32 v90, s38, v2
	v_add_u32_e32 v32, s3, v4
	v_mad_i64_i32 v[30:31], s[38:39], v30, s35, v[28:29]
	v_add_u32_e32 v36, s3, v63
	v_add_u32_e32 v34, s14, v78
	v_add_u32_e32 v40, s3, v79
	v_add_u32_e32 v38, s14, v80
	v_add_u32_e32 v44, s3, v81
	v_add_u32_e32 v42, s14, v82
	v_add_u32_e32 v64, s3, v83
	v_add_u32_e32 v46, s14, v84
	v_add_u32_e32 v68, s3, v85
	v_add_u32_e32 v66, s14, v86
	v_add_u32_e32 v72, s3, v87
	v_add_u32_e32 v70, s14, v88
	v_add_u32_e32 v76, s3, v89
	v_add_u32_e32 v74, s14, v90
	v_mad_i64_i32 v[32:33], s[38:39], v32, s35, v[28:29]
	v_mad_i64_i32 v[34:35], s[38:39], v34, s35, v[28:29]
	v_mad_i64_i32 v[36:37], s[38:39], v36, s35, v[28:29]
	v_mad_i64_i32 v[38:39], s[38:39], v38, s35, v[28:29]
	v_mad_i64_i32 v[40:41], s[38:39], v40, s35, v[28:29]
	v_mad_i64_i32 v[42:43], s[38:39], v42, s35, v[28:29]
	v_mad_i64_i32 v[44:45], s[38:39], v44, s35, v[28:29]
	v_mad_i64_i32 v[46:47], s[38:39], v46, s35, v[28:29]
	v_mad_i64_i32 v[64:65], s[38:39], v64, s35, v[28:29]
	v_mad_i64_i32 v[66:67], s[38:39], v66, s35, v[28:29]
	v_mad_i64_i32 v[68:69], s[38:39], v68, s35, v[28:29]
	v_mad_i64_i32 v[70:71], s[38:39], v70, s35, v[28:29]
	v_mad_i64_i32 v[72:73], s[38:39], v72, s35, v[28:29]
	v_mad_i64_i32 v[74:75], s[38:39], v74, s35, v[28:29]
	v_mad_i64_i32 v[76:77], s[38:39], v76, s35, v[28:29]
	global_load_dword v91, v[30:31], off nt
	global_load_dword v92, v[32:33], off nt
	global_load_dword v93, v[34:35], off nt
	global_load_dword v94, v[36:37], off nt
	global_load_dword v95, v[38:39], off nt
	global_load_dword v96, v[40:41], off nt
	global_load_dword v97, v[42:43], off nt
	global_load_dword v98, v[44:45], off nt
	global_load_dword v99, v[46:47], off nt
	global_load_dword v100, v[64:65], off nt
	global_load_dword v101, v[66:67], off nt
	global_load_dword v102, v[68:69], off nt
	global_load_dword v103, v[70:71], off nt
	global_load_dword v104, v[72:73], off nt
	global_load_dword v105, v[74:75], off nt
	global_load_dword v106, v[76:77], off nt
	s_add_i32 s15, s15, 16
	s_add_i32 s13, s13, 16
	s_add_i32 s36, s36, -16
	v_mad_u64_u32 v[30:31], s[38:39], v27, s18, v[12:13]
	s_cmp_lg_u32 s36, 0
	v_mad_u64_u32 v[32:33], s[38:39], v4, s18, v[12:13]
	v_mad_u64_u32 v[34:35], s[38:39], v78, s18, v[12:13]
	v_mad_u64_u32 v[36:37], s[38:39], v63, s18, v[12:13]
	v_mad_u64_u32 v[38:39], s[38:39], v80, s18, v[12:13]
	v_mad_u64_u32 v[40:41], s[38:39], v79, s18, v[12:13]
	v_mad_u64_u32 v[42:43], s[38:39], v82, s18, v[12:13]
	v_mad_u64_u32 v[44:45], s[38:39], v81, s18, v[12:13]
	v_mad_u64_u32 v[46:47], s[38:39], v84, s18, v[12:13]
	v_mad_u64_u32 v[64:65], s[38:39], v83, s18, v[12:13]
	v_mad_u64_u32 v[66:67], s[38:39], v86, s18, v[12:13]
	v_mad_u64_u32 v[68:69], s[38:39], v85, s18, v[12:13]
	v_mad_u64_u32 v[70:71], s[38:39], v88, s18, v[12:13]
	v_mad_u64_u32 v[72:73], s[38:39], v87, s18, v[12:13]
	v_mad_u64_u32 v[74:75], s[38:39], v90, s18, v[12:13]
	v_mad_u64_u32 v[76:77], s[38:39], v89, s18, v[12:13]
	s_waitcnt vmcnt(15)
	ds_write_b32 v30, v91
	s_waitcnt vmcnt(14)
	ds_write_b32 v32, v92
	s_waitcnt vmcnt(13)
	ds_write_b32 v34, v93
	s_waitcnt vmcnt(12)
	ds_write_b32 v36, v94
	s_waitcnt vmcnt(11)
	ds_write_b32 v38, v95
	s_waitcnt vmcnt(10)
	ds_write_b32 v40, v96
	s_waitcnt vmcnt(9)
	ds_write_b32 v42, v97
	s_waitcnt vmcnt(8)
	ds_write_b32 v44, v98
	s_waitcnt vmcnt(7)
	ds_write_b32 v46, v99
	s_waitcnt vmcnt(6)
	ds_write_b32 v64, v100
	s_waitcnt vmcnt(5)
	ds_write_b32 v66, v101
	s_waitcnt vmcnt(4)
	ds_write_b32 v68, v102
	s_waitcnt vmcnt(3)
	ds_write_b32 v70, v103
	s_waitcnt vmcnt(2)
	ds_write_b32 v72, v104
	s_waitcnt vmcnt(1)
	ds_write_b32 v74, v105
	s_waitcnt vmcnt(0)
	ds_write_b32 v76, v106
	s_cbranch_scc1 .LBB0_70
; #define LAS __attribute__((address_space(3)))
; __device__ __forceinline__ unsigned cvt_pk(float lo, float hi) { f32x2_t v = {lo, hi}; bf16x2_t b = __builtin_convertvector(v, bf16x2_t); return __builtin_bit_cast(unsigned, b); }
; __device__ __forceinline__ void transpose_item(const float* __restrict__ W, int ld_src, int k0, int n0src, const float* __restrict__ kscale, bf16_t* __restrict__ WT, int ldt, int n0dst, LAS float* scr, int lane) {
;     ...
;     asm volatile("s_waitcnt lgkmcnt(0)" ::: "memory"); __builtin_amdgcn_wave_barrier();
;     const int c = lane & 7;
; #pragma unroll
;     for (int jn = 0; jn < 4; ++jn) { const int n = (lane >> 3) + 8 * jn; const LAS float* s = scr + (8 * c) * 33 + n;
;         u32x4 o; o.x = cvt_pk(s[0 * 33], s[1 * 33]); o.y = cvt_pk(s[2 * 33], s[3 * 33]); o.z = cvt_pk(s[4 * 33], s[5 * 33]); o.w = cvt_pk(s[6 * 33], s[7 * 33]);
;         *(u32x4*)(WT + (size_t)(n0dst + n) * ldt + k0 + 8 * c) = o; }
;     asm volatile("s_waitcnt lgkmcnt(0)" ::: "memory"); __builtin_amdgcn_wave_barrier();
; __global__ void __launch_bounds__(512, 2) mk_fwd(Args args) {
;     ...
;                 transpose_item(w_in + (size_t)L * DM * NIN, NIN, kb * 64, n0, nullptr, WIN + (size_t)L * NINP * DM, DM, n0 < NMIX ? n0 : n0 + (NMIXP - NMIX), scr, lane); continue; } r -= I_IN;
	s_mul_hi_i32 s3, s12, 0x3800000
	s_mul_i32 s12, s12, 0x3800000
	s_add_u32 s12, s6, s12
	s_addc_u32 s13, s7, s3
	s_add_i32 s3, s2, 0xc0
	s_cmpk_lt_i32 s0, 0x9a
	s_cselect_b32 s0, s2, s3
	s_waitcnt lgkmcnt(0)
	s_ashr_i32 s15, s14, 31
	ds_read2_b32 v[32:33], v7 offset0:33 offset1:41
	ds_read2_b32 v[34:35], v7 offset1:8
	ds_read2_b32 v[36:37], v7 offset0:66 offset1:74
	ds_read2_b32 v[38:39], v7 offset0:99 offset1:107
	ds_read2_b32 v[40:41], v7 offset0:132 offset1:140
	ds_read2_b32 v[42:43], v7 offset0:165 offset1:173
	ds_read2_b32 v[44:45], v7 offset0:198 offset1:206
	ds_read2_b32 v[46:47], v7 offset0:231 offset1:239
	s_lshl_b64 s[2:3], s[14:15], 1
	s_add_u32 s2, s12, s2
	v_or_b32_e32 v66, s0, v3
	s_addc_u32 s3, s13, s3
	v_lshlrev_b32_e32 v4, 1, v14
	v_ashrrev_i32_e32 v67, 31, v66
	v_lshl_add_u64 v[64:65], s[2:3], 0, v[4:5]
	v_lshlrev_b64 v[66:67], 12, v[66:67]
	s_waitcnt lgkmcnt(6)
	v_cvt_pk_bf16_f32 v28, v34, v32
	s_waitcnt lgkmcnt(4)
	v_cvt_pk_bf16_f32 v29, v36, v38
	s_waitcnt lgkmcnt(2)
	v_cvt_pk_bf16_f32 v30, v40, v42
	s_waitcnt lgkmcnt(0)
	v_cvt_pk_bf16_f32 v31, v44, v46
	v_lshl_add_u64 v[66:67], v[64:65], 0, v[66:67]
	v_or_b32_e32 v32, s0, v9
	global_store_dwordx4 v[66:67], v[28:31], off
	v_readlane_b32 s40, v254, 34
	v_readlane_b32 s41, v254, 35
	v_cvt_pk_bf16_f32 v28, v35, v33
	v_ashrrev_i32_e32 v33, 31, v32
	v_cvt_pk_bf16_f32 v29, v37, v39
	v_cvt_pk_bf16_f32 v30, v41, v43
	v_cvt_pk_bf16_f32 v31, v45, v47
	v_lshlrev_b64 v[32:33], 12, v[32:33]
	ds_read2_b32 v[34:35], v7 offset0:49 offset1:57
	ds_read2_b32 v[36:37], v7 offset0:16 offset1:24
	ds_read2_b32 v[38:39], v7 offset0:82 offset1:90
	ds_read2_b32 v[40:41], v7 offset0:115 offset1:123
	ds_read2_b32 v[42:43], v7 offset0:148 offset1:156
	ds_read2_b32 v[44:45], v7 offset0:181 offset1:189
	ds_read2_b32 v[46:47], v7 offset0:214 offset1:222
	ds_read2_b32 v[66:67], v7 offset0:247 offset1:255
	v_lshl_add_u64 v[32:33], v[64:65], 0, v[32:33]
	global_store_dwordx4 v[32:33], v[28:31], off
	v_or_b32_e32 v32, s0, v11
	v_ashrrev_i32_e32 v33, 31, v32
	v_lshlrev_b64 v[32:33], 12, v[32:33]
	s_waitcnt lgkmcnt(6)
	v_cvt_pk_bf16_f32 v28, v36, v34
	s_waitcnt lgkmcnt(4)
	v_cvt_pk_bf16_f32 v29, v38, v40
	s_waitcnt lgkmcnt(2)
	v_cvt_pk_bf16_f32 v30, v42, v44
	s_waitcnt lgkmcnt(0)
	v_cvt_pk_bf16_f32 v31, v46, v66
	v_lshl_add_u64 v[32:33], v[64:65], 0, v[32:33]
	global_store_dwordx4 v[32:33], v[28:31], off
	v_or_b32_e32 v32, s0, v13
	v_ashrrev_i32_e32 v33, 31, v32
	v_lshlrev_b64 v[32:33], 12, v[32:33]
	v_cvt_pk_bf16_f32 v28, v37, v35
	v_cvt_pk_bf16_f32 v29, v39, v41
	v_cvt_pk_bf16_f32 v30, v43, v45
	v_cvt_pk_bf16_f32 v31, v47, v67
	v_lshl_add_u64 v[32:33], v[64:65], 0, v[32:33]
	global_store_dwordx4 v[32:33], v[28:31], off
	s_waitcnt lgkmcnt(0)
	v_readlane_b32 s42, v254, 36
	v_readlane_b32 s43, v254, 37
	v_readlane_b32 s44, v254, 38
	v_readlane_b32 s45, v254, 39
	v_readlane_b32 s46, v254, 40
	v_readlane_b32 s47, v254, 41
	v_readlane_b32 s48, v254, 42
	v_readlane_b32 s49, v254, 43
	v_readlane_b32 s50, v254, 44
	v_readlane_b32 s51, v254, 45
	v_readlane_b32 s52, v254, 46
	v_readlane_b32 s53, v254, 47
	v_readlane_b32 s54, v254, 48
	v_readlane_b32 s55, v254, 49
	s_branch .LBB0_7
